# gate scores on f32 MFMA (v_mfma_f32_32x32x2_f32) instead of VALU pk_fma fed by broadcast LDS reads
# baseline (speedup 1.0000x reference)
.LBB0_1101:
	s_or_b64 exec, exec, s[2:3]
	s_ashr_i32 s2, s64, 5
	v_lshl_add_u32 v4, s15, 8, v0
	s_ashr_i32 s3, s2, 31
	s_lshl_b64 s[2:3], s[2:3], 13
	v_ashrrev_i32_e32 v5, 31, v4
	s_cmp_eq_u32 s15, 0
	v_lshl_add_u64 v[4:5], s[2:3], 0, v[4:5]
	s_waitcnt lgkmcnt(0)
	s_barrier
	s_cbranch_scc1 .LBB0_1111
	v_lshlrev_b64 v[6:7], 7, v[4:5]
	v_lshl_add_u64 v[6:7], s[6:7], 0, v[6:7]
	global_load_dwordx4 v[10:13], v[6:7], off
	global_load_dwordx4 v[18:21], v[6:7], off offset:16
	global_load_dwordx4 v[26:29], v[6:7], off offset:32
	global_load_dwordx4 v[34:37], v[6:7], off offset:48
	global_load_dwordx4 v[42:45], v[6:7], off offset:64
	global_load_dwordx4 v[50:53], v[6:7], off offset:80
	global_load_dwordx4 v[58:61], v[6:7], off offset:96
	global_load_dwordx4 v[66:69], v[6:7], off offset:112
	v_mov_b32_e32 v77, 0xff
	s_mov_b32 s15, 0
	v_mov_b32_e32 v76, 0xff61b1e6
	s_mov_b32 s33, 16
	v_mov_b32_e32 v75, 0xff61b1e6
	v_mov_b32_e32 v73, 0xff
	v_mov_b32_e32 v74, 0xff
	v_mov_b32_e32 v78, 0xff61b1e6
	s_waitcnt vmcnt(7)
	v_lshlrev_b32_e32 v6, 16, v10
	v_and_b32_e32 v7, 0xffff0000, v10
	v_lshlrev_b32_e32 v8, 16, v11
	v_and_b32_e32 v9, 0xffff0000, v11
	v_lshlrev_b32_e32 v10, 16, v12
	v_and_b32_e32 v11, 0xffff0000, v12
	v_lshlrev_b32_e32 v12, 16, v13
	v_and_b32_e32 v13, 0xffff0000, v13
	s_waitcnt vmcnt(6)
	v_lshlrev_b32_e32 v14, 16, v18
	v_and_b32_e32 v15, 0xffff0000, v18
	v_lshlrev_b32_e32 v16, 16, v19
	v_and_b32_e32 v17, 0xffff0000, v19
	v_lshlrev_b32_e32 v18, 16, v20
	v_and_b32_e32 v19, 0xffff0000, v20
	v_lshlrev_b32_e32 v20, 16, v21
	v_and_b32_e32 v21, 0xffff0000, v21
	s_waitcnt vmcnt(5)
	v_lshlrev_b32_e32 v22, 16, v26
	v_and_b32_e32 v23, 0xffff0000, v26
	v_lshlrev_b32_e32 v24, 16, v27
	v_and_b32_e32 v25, 0xffff0000, v27
	v_lshlrev_b32_e32 v26, 16, v28
	v_and_b32_e32 v27, 0xffff0000, v28
	v_lshlrev_b32_e32 v28, 16, v29
	v_and_b32_e32 v29, 0xffff0000, v29
	s_waitcnt vmcnt(4)
	v_lshlrev_b32_e32 v30, 16, v34
	v_and_b32_e32 v31, 0xffff0000, v34
	v_lshlrev_b32_e32 v32, 16, v35
	v_and_b32_e32 v33, 0xffff0000, v35
	v_lshlrev_b32_e32 v34, 16, v36
	v_and_b32_e32 v35, 0xffff0000, v36
	v_lshlrev_b32_e32 v36, 16, v37
	v_and_b32_e32 v37, 0xffff0000, v37
	s_waitcnt vmcnt(3)
	v_lshlrev_b32_e32 v38, 16, v42
	v_and_b32_e32 v39, 0xffff0000, v42
	v_lshlrev_b32_e32 v40, 16, v43
	v_and_b32_e32 v41, 0xffff0000, v43
	v_lshlrev_b32_e32 v42, 16, v44
	v_and_b32_e32 v43, 0xffff0000, v44
	v_lshlrev_b32_e32 v44, 16, v45
	v_and_b32_e32 v45, 0xffff0000, v45
	s_waitcnt vmcnt(2)
	v_lshlrev_b32_e32 v46, 16, v50
	v_and_b32_e32 v47, 0xffff0000, v50
	v_lshlrev_b32_e32 v48, 16, v51
	v_and_b32_e32 v49, 0xffff0000, v51
	v_lshlrev_b32_e32 v50, 16, v52
	v_and_b32_e32 v51, 0xffff0000, v52
	v_lshlrev_b32_e32 v52, 16, v53
	v_and_b32_e32 v53, 0xffff0000, v53
	s_waitcnt vmcnt(1)
	v_lshlrev_b32_e32 v54, 16, v58
	v_and_b32_e32 v55, 0xffff0000, v58
	v_lshlrev_b32_e32 v56, 16, v59
	v_and_b32_e32 v57, 0xffff0000, v59
	v_lshlrev_b32_e32 v58, 16, v60
	v_and_b32_e32 v59, 0xffff0000, v60
	v_lshlrev_b32_e32 v60, 16, v61
	v_and_b32_e32 v61, 0xffff0000, v61
	s_waitcnt vmcnt(0)
	v_lshlrev_b32_e32 v62, 16, v66
	v_and_b32_e32 v63, 0xffff0000, v66
	v_lshlrev_b32_e32 v64, 16, v67
	v_and_b32_e32 v65, 0xffff0000, v67
	v_lshlrev_b32_e32 v66, 16, v68
	v_and_b32_e32 v67, 0xffff0000, v68
	v_lshlrev_b32_e32 v68, 16, v69
	v_and_b32_e32 v69, 0xffff0000, v69
	v_and_b32_e32 v81, 63, v0
	v_lshrrev_b32_e32 v79, 5, v81
	v_and_b32_e32 v81, 31, v81
	v_lshlrev_b32_e32 v81, 8, v81
	v_lshl_add_u32 v81, v79, 7, v81
	v_add_u32_e32 v81, 16, v81
	ds_read_b128 v[100:103], v81
	ds_read_b128 v[104:107], v81 offset:16
	ds_read_b128 v[108:111], v81 offset:32
	ds_read_b128 v[112:115], v81 offset:48
	ds_read_b128 v[116:119], v81 offset:64
	ds_read_b128 v[120:123], v81 offset:80
	ds_read_b128 v[124:127], v81 offset:96
	ds_read_b128 v[128:131], v81 offset:112
	s_nop 1
	v_permlane32_swap_b32_e32 v6, v38
	v_permlane32_swap_b32_e32 v7, v39
	v_permlane32_swap_b32_e32 v8, v40
	v_permlane32_swap_b32_e32 v9, v41
	v_permlane32_swap_b32_e32 v10, v42
	v_permlane32_swap_b32_e32 v11, v43
	v_permlane32_swap_b32_e32 v12, v44
	v_permlane32_swap_b32_e32 v13, v45
	v_permlane32_swap_b32_e32 v14, v46
	v_permlane32_swap_b32_e32 v15, v47
	v_permlane32_swap_b32_e32 v16, v48
	v_permlane32_swap_b32_e32 v17, v49
	v_permlane32_swap_b32_e32 v18, v50
	v_permlane32_swap_b32_e32 v19, v51
	v_permlane32_swap_b32_e32 v20, v52
	v_permlane32_swap_b32_e32 v21, v53
	v_permlane32_swap_b32_e32 v22, v54
	v_permlane32_swap_b32_e32 v23, v55
	v_permlane32_swap_b32_e32 v24, v56
	v_permlane32_swap_b32_e32 v25, v57
	v_permlane32_swap_b32_e32 v26, v58
	v_permlane32_swap_b32_e32 v27, v59
	v_permlane32_swap_b32_e32 v28, v60
	v_permlane32_swap_b32_e32 v29, v61
	v_permlane32_swap_b32_e32 v30, v62
	v_permlane32_swap_b32_e32 v31, v63
	v_permlane32_swap_b32_e32 v32, v64
	v_permlane32_swap_b32_e32 v33, v65
	v_permlane32_swap_b32_e32 v34, v66
	v_permlane32_swap_b32_e32 v35, v67
	v_permlane32_swap_b32_e32 v36, v68
	v_permlane32_swap_b32_e32 v37, v69
	s_waitcnt lgkmcnt(0)
	v_mfma_f32_32x32x2_f32 v[146:161], v100, v6, 0
	v_mfma_f32_32x32x2_f32 v[162:177], v100, v38, 0
	v_mfma_f32_32x32x2_f32 v[146:161], v101, v7, v[146:161]
	v_mfma_f32_32x32x2_f32 v[162:177], v101, v39, v[162:177]
	v_mfma_f32_32x32x2_f32 v[146:161], v102, v8, v[146:161]
	v_mfma_f32_32x32x2_f32 v[162:177], v102, v40, v[162:177]
	v_mfma_f32_32x32x2_f32 v[146:161], v103, v9, v[146:161]
	v_mfma_f32_32x32x2_f32 v[162:177], v103, v41, v[162:177]
	v_mfma_f32_32x32x2_f32 v[146:161], v104, v10, v[146:161]
	v_mfma_f32_32x32x2_f32 v[162:177], v104, v42, v[162:177]
	v_mfma_f32_32x32x2_f32 v[146:161], v105, v11, v[146:161]
	v_mfma_f32_32x32x2_f32 v[162:177], v105, v43, v[162:177]
	v_mfma_f32_32x32x2_f32 v[146:161], v106, v12, v[146:161]
	v_mfma_f32_32x32x2_f32 v[162:177], v106, v44, v[162:177]
	v_mfma_f32_32x32x2_f32 v[146:161], v107, v13, v[146:161]
	v_mfma_f32_32x32x2_f32 v[162:177], v107, v45, v[162:177]
	v_mfma_f32_32x32x2_f32 v[146:161], v108, v14, v[146:161]
	v_mfma_f32_32x32x2_f32 v[162:177], v108, v46, v[162:177]
	v_mfma_f32_32x32x2_f32 v[146:161], v109, v15, v[146:161]
	v_mfma_f32_32x32x2_f32 v[162:177], v109, v47, v[162:177]
	v_mfma_f32_32x32x2_f32 v[146:161], v110, v16, v[146:161]
	v_mfma_f32_32x32x2_f32 v[162:177], v110, v48, v[162:177]
	v_mfma_f32_32x32x2_f32 v[146:161], v111, v17, v[146:161]
	v_mfma_f32_32x32x2_f32 v[162:177], v111, v49, v[162:177]
	v_mfma_f32_32x32x2_f32 v[146:161], v112, v18, v[146:161]
	v_mfma_f32_32x32x2_f32 v[162:177], v112, v50, v[162:177]
	v_mfma_f32_32x32x2_f32 v[146:161], v113, v19, v[146:161]
	v_mfma_f32_32x32x2_f32 v[162:177], v113, v51, v[162:177]
	v_mfma_f32_32x32x2_f32 v[146:161], v114, v20, v[146:161]
	v_mfma_f32_32x32x2_f32 v[162:177], v114, v52, v[162:177]
	v_mfma_f32_32x32x2_f32 v[146:161], v115, v21, v[146:161]
	v_mfma_f32_32x32x2_f32 v[162:177], v115, v53, v[162:177]
	v_mfma_f32_32x32x2_f32 v[146:161], v116, v22, v[146:161]
	v_mfma_f32_32x32x2_f32 v[162:177], v116, v54, v[162:177]
	v_mfma_f32_32x32x2_f32 v[146:161], v117, v23, v[146:161]
	v_mfma_f32_32x32x2_f32 v[162:177], v117, v55, v[162:177]
	v_mfma_f32_32x32x2_f32 v[146:161], v118, v24, v[146:161]
	v_mfma_f32_32x32x2_f32 v[162:177], v118, v56, v[162:177]
	v_mfma_f32_32x32x2_f32 v[146:161], v119, v25, v[146:161]
	v_mfma_f32_32x32x2_f32 v[162:177], v119, v57, v[162:177]
	v_mfma_f32_32x32x2_f32 v[146:161], v120, v26, v[146:161]
	v_mfma_f32_32x32x2_f32 v[162:177], v120, v58, v[162:177]
	v_mfma_f32_32x32x2_f32 v[146:161], v121, v27, v[146:161]
	v_mfma_f32_32x32x2_f32 v[162:177], v121, v59, v[162:177]
	v_mfma_f32_32x32x2_f32 v[146:161], v122, v28, v[146:161]
	v_mfma_f32_32x32x2_f32 v[162:177], v122, v60, v[162:177]
	v_mfma_f32_32x32x2_f32 v[146:161], v123, v29, v[146:161]
	v_mfma_f32_32x32x2_f32 v[162:177], v123, v61, v[162:177]
	v_mfma_f32_32x32x2_f32 v[146:161], v124, v30, v[146:161]
	v_mfma_f32_32x32x2_f32 v[162:177], v124, v62, v[162:177]
	v_mfma_f32_32x32x2_f32 v[146:161], v125, v31, v[146:161]
	v_mfma_f32_32x32x2_f32 v[162:177], v125, v63, v[162:177]
	v_mfma_f32_32x32x2_f32 v[146:161], v126, v32, v[146:161]
	v_mfma_f32_32x32x2_f32 v[162:177], v126, v64, v[162:177]
	v_mfma_f32_32x32x2_f32 v[146:161], v127, v33, v[146:161]
	v_mfma_f32_32x32x2_f32 v[162:177], v127, v65, v[162:177]
	v_mfma_f32_32x32x2_f32 v[146:161], v128, v34, v[146:161]
	v_mfma_f32_32x32x2_f32 v[162:177], v128, v66, v[162:177]
	v_mfma_f32_32x32x2_f32 v[146:161], v129, v35, v[146:161]
	v_mfma_f32_32x32x2_f32 v[162:177], v129, v67, v[162:177]
	v_mfma_f32_32x32x2_f32 v[146:161], v130, v36, v[146:161]
	v_mfma_f32_32x32x2_f32 v[162:177], v130, v68, v[162:177]
	v_mfma_f32_32x32x2_f32 v[146:161], v131, v37, v[146:161]
	v_mfma_f32_32x32x2_f32 v[162:177], v131, v69, v[162:177]
	v_mov_b32_e32 v73, 0xff61b1e6
	v_mov_b32_e32 v74, 0xff61b1e6
	v_mov_b32_e32 v75, 0xff61b1e6
	v_mov_b32_e32 v76, 0xff
	v_mov_b32_e32 v77, 0xff
	v_mov_b32_e32 v78, 0xff
	s_nop 7
	s_nop 7
	s_nop 7
	v_permlane32_swap_b32_e32 v146, v162
	v_permlane32_swap_b32_e32 v147, v163
	v_permlane32_swap_b32_e32 v148, v164
	v_permlane32_swap_b32_e32 v149, v165
	v_permlane32_swap_b32_e32 v150, v166
	v_permlane32_swap_b32_e32 v151, v167
	v_permlane32_swap_b32_e32 v152, v168
	v_permlane32_swap_b32_e32 v153, v169
	v_permlane32_swap_b32_e32 v154, v170
	v_permlane32_swap_b32_e32 v155, v171
	v_permlane32_swap_b32_e32 v156, v172
	v_permlane32_swap_b32_e32 v157, v173
	v_permlane32_swap_b32_e32 v158, v174
	v_permlane32_swap_b32_e32 v159, v175
	v_permlane32_swap_b32_e32 v160, v176
	v_permlane32_swap_b32_e32 v161, v177
	s_cmp_eq_u32 s14, 0
	s_cbranch_scc1 .Lgm_done
	v_cmp_gt_f32_e32 vcc, v146, v75
	v_cmp_gt_f32_e64 s[4:5], v146, v74
	v_cmp_gt_f32_e64 s[2:3], v146, v73
	v_cndmask_b32_e32 v75, v75, v146, vcc
	v_cndmask_b32_e64 v78, v78, 0, vcc
	v_cndmask_b32_e64 v75, v75, v74, s[4:5]
	v_cndmask_b32_e64 v78, v78, v77, s[4:5]
	v_cndmask_b32_e64 v74, v74, v146, s[4:5]
	v_cndmask_b32_e64 v77, v77, 0, s[4:5]
	v_cndmask_b32_e64 v74, v74, v73, s[2:3]
	v_cndmask_b32_e64 v77, v77, v76, s[2:3]
	v_cndmask_b32_e64 v73, v73, v146, s[2:3]
	v_cndmask_b32_e64 v76, v76, 0, s[2:3]
	s_cmp_eq_u32 s14, 1
	s_cbranch_scc1 .Lgm_done
	v_cmp_gt_f32_e32 vcc, v147, v75
	v_cmp_gt_f32_e64 s[4:5], v147, v74
	v_cmp_gt_f32_e64 s[2:3], v147, v73
	v_cndmask_b32_e32 v75, v75, v147, vcc
	v_cndmask_b32_e64 v78, v78, 1, vcc
	v_cndmask_b32_e64 v75, v75, v74, s[4:5]
	v_cndmask_b32_e64 v78, v78, v77, s[4:5]
	v_cndmask_b32_e64 v74, v74, v147, s[4:5]
	v_cndmask_b32_e64 v77, v77, 1, s[4:5]
	v_cndmask_b32_e64 v74, v74, v73, s[2:3]
	v_cndmask_b32_e64 v77, v77, v76, s[2:3]
	v_cndmask_b32_e64 v73, v73, v147, s[2:3]
	v_cndmask_b32_e64 v76, v76, 1, s[2:3]
	s_cmp_eq_u32 s14, 2
	s_cbranch_scc1 .Lgm_done
	v_cmp_gt_f32_e32 vcc, v148, v75
	v_cmp_gt_f32_e64 s[4:5], v148, v74
	v_cmp_gt_f32_e64 s[2:3], v148, v73
	v_cndmask_b32_e32 v75, v75, v148, vcc
	v_cndmask_b32_e64 v78, v78, 2, vcc
	v_cndmask_b32_e64 v75, v75, v74, s[4:5]
	v_cndmask_b32_e64 v78, v78, v77, s[4:5]
	v_cndmask_b32_e64 v74, v74, v148, s[4:5]
	v_cndmask_b32_e64 v77, v77, 2, s[4:5]
	v_cndmask_b32_e64 v74, v74, v73, s[2:3]
	v_cndmask_b32_e64 v77, v77, v76, s[2:3]
	v_cndmask_b32_e64 v73, v73, v148, s[2:3]
	v_cndmask_b32_e64 v76, v76, 2, s[2:3]
	s_cmp_eq_u32 s14, 3
	s_cbranch_scc1 .Lgm_done
	v_cmp_gt_f32_e32 vcc, v149, v75
	v_cmp_gt_f32_e64 s[4:5], v149, v74
	v_cmp_gt_f32_e64 s[2:3], v149, v73
	v_cndmask_b32_e32 v75, v75, v149, vcc
	v_cndmask_b32_e64 v78, v78, 3, vcc
	v_cndmask_b32_e64 v75, v75, v74, s[4:5]
	v_cndmask_b32_e64 v78, v78, v77, s[4:5]
	v_cndmask_b32_e64 v74, v74, v149, s[4:5]
	v_cndmask_b32_e64 v77, v77, 3, s[4:5]
	v_cndmask_b32_e64 v74, v74, v73, s[2:3]
	v_cndmask_b32_e64 v77, v77, v76, s[2:3]
	v_cndmask_b32_e64 v73, v73, v149, s[2:3]
	v_cndmask_b32_e64 v76, v76, 3, s[2:3]
	s_cmp_eq_u32 s14, 4
	s_cbranch_scc1 .Lgm_done
	v_cmp_gt_f32_e32 vcc, v162, v75
	v_cmp_gt_f32_e64 s[4:5], v162, v74
	v_cmp_gt_f32_e64 s[2:3], v162, v73
	v_cndmask_b32_e32 v75, v75, v162, vcc
	v_cndmask_b32_e64 v78, v78, 4, vcc
	v_cndmask_b32_e64 v75, v75, v74, s[4:5]
	v_cndmask_b32_e64 v78, v78, v77, s[4:5]
	v_cndmask_b32_e64 v74, v74, v162, s[4:5]
	v_cndmask_b32_e64 v77, v77, 4, s[4:5]
	v_cndmask_b32_e64 v74, v74, v73, s[2:3]
	v_cndmask_b32_e64 v77, v77, v76, s[2:3]
	v_cndmask_b32_e64 v73, v73, v162, s[2:3]
	v_cndmask_b32_e64 v76, v76, 4, s[2:3]
	s_cmp_eq_u32 s14, 5
	s_cbranch_scc1 .Lgm_done
	v_cmp_gt_f32_e32 vcc, v163, v75
	v_cmp_gt_f32_e64 s[4:5], v163, v74
	v_cmp_gt_f32_e64 s[2:3], v163, v73
	v_cndmask_b32_e32 v75, v75, v163, vcc
	v_cndmask_b32_e64 v78, v78, 5, vcc
	v_cndmask_b32_e64 v75, v75, v74, s[4:5]
	v_cndmask_b32_e64 v78, v78, v77, s[4:5]
	v_cndmask_b32_e64 v74, v74, v163, s[4:5]
	v_cndmask_b32_e64 v77, v77, 5, s[4:5]
	v_cndmask_b32_e64 v74, v74, v73, s[2:3]
	v_cndmask_b32_e64 v77, v77, v76, s[2:3]
	v_cndmask_b32_e64 v73, v73, v163, s[2:3]
	v_cndmask_b32_e64 v76, v76, 5, s[2:3]
	s_cmp_eq_u32 s14, 6
	s_cbranch_scc1 .Lgm_done
	v_cmp_gt_f32_e32 vcc, v164, v75
	v_cmp_gt_f32_e64 s[4:5], v164, v74
	v_cmp_gt_f32_e64 s[2:3], v164, v73
	v_cndmask_b32_e32 v75, v75, v164, vcc
	v_cndmask_b32_e64 v78, v78, 6, vcc
	v_cndmask_b32_e64 v75, v75, v74, s[4:5]
	v_cndmask_b32_e64 v78, v78, v77, s[4:5]
	v_cndmask_b32_e64 v74, v74, v164, s[4:5]
	v_cndmask_b32_e64 v77, v77, 6, s[4:5]
	v_cndmask_b32_e64 v74, v74, v73, s[2:3]
	v_cndmask_b32_e64 v77, v77, v76, s[2:3]
	v_cndmask_b32_e64 v73, v73, v164, s[2:3]
	v_cndmask_b32_e64 v76, v76, 6, s[2:3]
	s_cmp_eq_u32 s14, 7
	s_cbranch_scc1 .Lgm_done
	v_cmp_gt_f32_e32 vcc, v165, v75
	v_cmp_gt_f32_e64 s[4:5], v165, v74
	v_cmp_gt_f32_e64 s[2:3], v165, v73
	v_cndmask_b32_e32 v75, v75, v165, vcc
	v_cndmask_b32_e64 v78, v78, 7, vcc
	v_cndmask_b32_e64 v75, v75, v74, s[4:5]
	v_cndmask_b32_e64 v78, v78, v77, s[4:5]
	v_cndmask_b32_e64 v74, v74, v165, s[4:5]
	v_cndmask_b32_e64 v77, v77, 7, s[4:5]
	v_cndmask_b32_e64 v74, v74, v73, s[2:3]
	v_cndmask_b32_e64 v77, v77, v76, s[2:3]
	v_cndmask_b32_e64 v73, v73, v165, s[2:3]
	v_cndmask_b32_e64 v76, v76, 7, s[2:3]
	s_cmp_eq_u32 s14, 8
	s_cbranch_scc1 .Lgm_done
	v_cmp_gt_f32_e32 vcc, v150, v75
	v_cmp_gt_f32_e64 s[4:5], v150, v74
	v_cmp_gt_f32_e64 s[2:3], v150, v73
	v_cndmask_b32_e32 v75, v75, v150, vcc
	v_cndmask_b32_e64 v78, v78, 8, vcc
	v_cndmask_b32_e64 v75, v75, v74, s[4:5]
	v_cndmask_b32_e64 v78, v78, v77, s[4:5]
	v_cndmask_b32_e64 v74, v74, v150, s[4:5]
	v_cndmask_b32_e64 v77, v77, 8, s[4:5]
	v_cndmask_b32_e64 v74, v74, v73, s[2:3]
	v_cndmask_b32_e64 v77, v77, v76, s[2:3]
	v_cndmask_b32_e64 v73, v73, v150, s[2:3]
	v_cndmask_b32_e64 v76, v76, 8, s[2:3]
	s_cmp_eq_u32 s14, 9
	s_cbranch_scc1 .Lgm_done
	v_cmp_gt_f32_e32 vcc, v151, v75
	v_cmp_gt_f32_e64 s[4:5], v151, v74
	v_cmp_gt_f32_e64 s[2:3], v151, v73
	v_cndmask_b32_e32 v75, v75, v151, vcc
	v_cndmask_b32_e64 v78, v78, 9, vcc
	v_cndmask_b32_e64 v75, v75, v74, s[4:5]
	v_cndmask_b32_e64 v78, v78, v77, s[4:5]
	v_cndmask_b32_e64 v74, v74, v151, s[4:5]
	v_cndmask_b32_e64 v77, v77, 9, s[4:5]
	v_cndmask_b32_e64 v74, v74, v73, s[2:3]
	v_cndmask_b32_e64 v77, v77, v76, s[2:3]
	v_cndmask_b32_e64 v73, v73, v151, s[2:3]
	v_cndmask_b32_e64 v76, v76, 9, s[2:3]
	s_cmp_eq_u32 s14, 10
	s_cbranch_scc1 .Lgm_done
	v_cmp_gt_f32_e32 vcc, v152, v75
	v_cmp_gt_f32_e64 s[4:5], v152, v74
	v_cmp_gt_f32_e64 s[2:3], v152, v73
	v_cndmask_b32_e32 v75, v75, v152, vcc
	v_cndmask_b32_e64 v78, v78, 10, vcc
	v_cndmask_b32_e64 v75, v75, v74, s[4:5]
	v_cndmask_b32_e64 v78, v78, v77, s[4:5]
	v_cndmask_b32_e64 v74, v74, v152, s[4:5]
	v_cndmask_b32_e64 v77, v77, 10, s[4:5]
	v_cndmask_b32_e64 v74, v74, v73, s[2:3]
	v_cndmask_b32_e64 v77, v77, v76, s[2:3]
	v_cndmask_b32_e64 v73, v73, v152, s[2:3]
	v_cndmask_b32_e64 v76, v76, 10, s[2:3]
	s_cmp_eq_u32 s14, 11
	s_cbranch_scc1 .Lgm_done
	v_cmp_gt_f32_e32 vcc, v153, v75
	v_cmp_gt_f32_e64 s[4:5], v153, v74
	v_cmp_gt_f32_e64 s[2:3], v153, v73
	v_cndmask_b32_e32 v75, v75, v153, vcc
	v_cndmask_b32_e64 v78, v78, 11, vcc
	v_cndmask_b32_e64 v75, v75, v74, s[4:5]
	v_cndmask_b32_e64 v78, v78, v77, s[4:5]
	v_cndmask_b32_e64 v74, v74, v153, s[4:5]
	v_cndmask_b32_e64 v77, v77, 11, s[4:5]
	v_cndmask_b32_e64 v74, v74, v73, s[2:3]
	v_cndmask_b32_e64 v77, v77, v76, s[2:3]
	v_cndmask_b32_e64 v73, v73, v153, s[2:3]
	v_cndmask_b32_e64 v76, v76, 11, s[2:3]
	s_cmp_eq_u32 s14, 12
	s_cbranch_scc1 .Lgm_done
	v_cmp_gt_f32_e32 vcc, v166, v75
	v_cmp_gt_f32_e64 s[4:5], v166, v74
	v_cmp_gt_f32_e64 s[2:3], v166, v73
	v_cndmask_b32_e32 v75, v75, v166, vcc
	v_cndmask_b32_e64 v78, v78, 12, vcc
	v_cndmask_b32_e64 v75, v75, v74, s[4:5]
	v_cndmask_b32_e64 v78, v78, v77, s[4:5]
	v_cndmask_b32_e64 v74, v74, v166, s[4:5]
	v_cndmask_b32_e64 v77, v77, 12, s[4:5]
	v_cndmask_b32_e64 v74, v74, v73, s[2:3]
	v_cndmask_b32_e64 v77, v77, v76, s[2:3]
	v_cndmask_b32_e64 v73, v73, v166, s[2:3]
	v_cndmask_b32_e64 v76, v76, 12, s[2:3]
	s_cmp_eq_u32 s14, 13
	s_cbranch_scc1 .Lgm_done
	v_cmp_gt_f32_e32 vcc, v167, v75
	v_cmp_gt_f32_e64 s[4:5], v167, v74
	v_cmp_gt_f32_e64 s[2:3], v167, v73
	v_cndmask_b32_e32 v75, v75, v167, vcc
	v_cndmask_b32_e64 v78, v78, 13, vcc
	v_cndmask_b32_e64 v75, v75, v74, s[4:5]
	v_cndmask_b32_e64 v78, v78, v77, s[4:5]
	v_cndmask_b32_e64 v74, v74, v167, s[4:5]
	v_cndmask_b32_e64 v77, v77, 13, s[4:5]
	v_cndmask_b32_e64 v74, v74, v73, s[2:3]
	v_cndmask_b32_e64 v77, v77, v76, s[2:3]
	v_cndmask_b32_e64 v73, v73, v167, s[2:3]
	v_cndmask_b32_e64 v76, v76, 13, s[2:3]
	s_cmp_eq_u32 s14, 14
	s_cbranch_scc1 .Lgm_done
	v_cmp_gt_f32_e32 vcc, v168, v75
	v_cmp_gt_f32_e64 s[4:5], v168, v74
	v_cmp_gt_f32_e64 s[2:3], v168, v73
	v_cndmask_b32_e32 v75, v75, v168, vcc
	v_cndmask_b32_e64 v78, v78, 14, vcc
	v_cndmask_b32_e64 v75, v75, v74, s[4:5]
	v_cndmask_b32_e64 v78, v78, v77, s[4:5]
	v_cndmask_b32_e64 v74, v74, v168, s[4:5]
	v_cndmask_b32_e64 v77, v77, 14, s[4:5]
	v_cndmask_b32_e64 v74, v74, v73, s[2:3]
	v_cndmask_b32_e64 v77, v77, v76, s[2:3]
	v_cndmask_b32_e64 v73, v73, v168, s[2:3]
	v_cndmask_b32_e64 v76, v76, 14, s[2:3]
	s_cmp_eq_u32 s14, 15
	s_cbranch_scc1 .Lgm_done
	v_cmp_gt_f32_e32 vcc, v169, v75
	v_cmp_gt_f32_e64 s[4:5], v169, v74
	v_cmp_gt_f32_e64 s[2:3], v169, v73
	v_cndmask_b32_e32 v75, v75, v169, vcc
	v_cndmask_b32_e64 v78, v78, 15, vcc
	v_cndmask_b32_e64 v75, v75, v74, s[4:5]
	v_cndmask_b32_e64 v78, v78, v77, s[4:5]
	v_cndmask_b32_e64 v74, v74, v169, s[4:5]
	v_cndmask_b32_e64 v77, v77, 15, s[4:5]
	v_cndmask_b32_e64 v74, v74, v73, s[2:3]
	v_cndmask_b32_e64 v77, v77, v76, s[2:3]
	v_cndmask_b32_e64 v73, v73, v169, s[2:3]
	v_cndmask_b32_e64 v76, v76, 15, s[2:3]
	s_cmp_eq_u32 s14, 16
	s_cbranch_scc1 .Lgm_done
	v_cmp_gt_f32_e32 vcc, v154, v75
	v_cmp_gt_f32_e64 s[4:5], v154, v74
	v_cmp_gt_f32_e64 s[2:3], v154, v73
	v_cndmask_b32_e32 v75, v75, v154, vcc
	v_cndmask_b32_e64 v78, v78, 16, vcc
	v_cndmask_b32_e64 v75, v75, v74, s[4:5]
	v_cndmask_b32_e64 v78, v78, v77, s[4:5]
	v_cndmask_b32_e64 v74, v74, v154, s[4:5]
	v_cndmask_b32_e64 v77, v77, 16, s[4:5]
	v_cndmask_b32_e64 v74, v74, v73, s[2:3]
	v_cndmask_b32_e64 v77, v77, v76, s[2:3]
	v_cndmask_b32_e64 v73, v73, v154, s[2:3]
	v_cndmask_b32_e64 v76, v76, 16, s[2:3]
	s_cmp_eq_u32 s14, 17
	s_cbranch_scc1 .Lgm_done
	v_cmp_gt_f32_e32 vcc, v155, v75
	v_cmp_gt_f32_e64 s[4:5], v155, v74
	v_cmp_gt_f32_e64 s[2:3], v155, v73
	v_cndmask_b32_e32 v75, v75, v155, vcc
	v_cndmask_b32_e64 v78, v78, 17, vcc
	v_cndmask_b32_e64 v75, v75, v74, s[4:5]
	v_cndmask_b32_e64 v78, v78, v77, s[4:5]
	v_cndmask_b32_e64 v74, v74, v155, s[4:5]
	v_cndmask_b32_e64 v77, v77, 17, s[4:5]
	v_cndmask_b32_e64 v74, v74, v73, s[2:3]
	v_cndmask_b32_e64 v77, v77, v76, s[2:3]
	v_cndmask_b32_e64 v73, v73, v155, s[2:3]
	v_cndmask_b32_e64 v76, v76, 17, s[2:3]
	s_cmp_eq_u32 s14, 18
	s_cbranch_scc1 .Lgm_done
	v_cmp_gt_f32_e32 vcc, v156, v75
	v_cmp_gt_f32_e64 s[4:5], v156, v74
	v_cmp_gt_f32_e64 s[2:3], v156, v73
	v_cndmask_b32_e32 v75, v75, v156, vcc
	v_cndmask_b32_e64 v78, v78, 18, vcc
	v_cndmask_b32_e64 v75, v75, v74, s[4:5]
	v_cndmask_b32_e64 v78, v78, v77, s[4:5]
	v_cndmask_b32_e64 v74, v74, v156, s[4:5]
	v_cndmask_b32_e64 v77, v77, 18, s[4:5]
	v_cndmask_b32_e64 v74, v74, v73, s[2:3]
	v_cndmask_b32_e64 v77, v77, v76, s[2:3]
	v_cndmask_b32_e64 v73, v73, v156, s[2:3]
	v_cndmask_b32_e64 v76, v76, 18, s[2:3]
	s_cmp_eq_u32 s14, 19
	s_cbranch_scc1 .Lgm_done
	v_cmp_gt_f32_e32 vcc, v157, v75
	v_cmp_gt_f32_e64 s[4:5], v157, v74
	v_cmp_gt_f32_e64 s[2:3], v157, v73
	v_cndmask_b32_e32 v75, v75, v157, vcc
	v_cndmask_b32_e64 v78, v78, 19, vcc
	v_cndmask_b32_e64 v75, v75, v74, s[4:5]
	v_cndmask_b32_e64 v78, v78, v77, s[4:5]
	v_cndmask_b32_e64 v74, v74, v157, s[4:5]
	v_cndmask_b32_e64 v77, v77, 19, s[4:5]
	v_cndmask_b32_e64 v74, v74, v73, s[2:3]
	v_cndmask_b32_e64 v77, v77, v76, s[2:3]
	v_cndmask_b32_e64 v73, v73, v157, s[2:3]
	v_cndmask_b32_e64 v76, v76, 19, s[2:3]
	s_cmp_eq_u32 s14, 20
	s_cbranch_scc1 .Lgm_done
	v_cmp_gt_f32_e32 vcc, v170, v75
	v_cmp_gt_f32_e64 s[4:5], v170, v74
	v_cmp_gt_f32_e64 s[2:3], v170, v73
	v_cndmask_b32_e32 v75, v75, v170, vcc
	v_cndmask_b32_e64 v78, v78, 20, vcc
	v_cndmask_b32_e64 v75, v75, v74, s[4:5]
	v_cndmask_b32_e64 v78, v78, v77, s[4:5]
	v_cndmask_b32_e64 v74, v74, v170, s[4:5]
	v_cndmask_b32_e64 v77, v77, 20, s[4:5]
	v_cndmask_b32_e64 v74, v74, v73, s[2:3]
	v_cndmask_b32_e64 v77, v77, v76, s[2:3]
	v_cndmask_b32_e64 v73, v73, v170, s[2:3]
	v_cndmask_b32_e64 v76, v76, 20, s[2:3]
	s_cmp_eq_u32 s14, 21
	s_cbranch_scc1 .Lgm_done
	v_cmp_gt_f32_e32 vcc, v171, v75
	v_cmp_gt_f32_e64 s[4:5], v171, v74
	v_cmp_gt_f32_e64 s[2:3], v171, v73
	v_cndmask_b32_e32 v75, v75, v171, vcc
	v_cndmask_b32_e64 v78, v78, 21, vcc
	v_cndmask_b32_e64 v75, v75, v74, s[4:5]
	v_cndmask_b32_e64 v78, v78, v77, s[4:5]
	v_cndmask_b32_e64 v74, v74, v171, s[4:5]
	v_cndmask_b32_e64 v77, v77, 21, s[4:5]
	v_cndmask_b32_e64 v74, v74, v73, s[2:3]
	v_cndmask_b32_e64 v77, v77, v76, s[2:3]
	v_cndmask_b32_e64 v73, v73, v171, s[2:3]
	v_cndmask_b32_e64 v76, v76, 21, s[2:3]
	s_cmp_eq_u32 s14, 22
	s_cbranch_scc1 .Lgm_done
	v_cmp_gt_f32_e32 vcc, v172, v75
	v_cmp_gt_f32_e64 s[4:5], v172, v74
	v_cmp_gt_f32_e64 s[2:3], v172, v73
	v_cndmask_b32_e32 v75, v75, v172, vcc
	v_cndmask_b32_e64 v78, v78, 22, vcc
	v_cndmask_b32_e64 v75, v75, v74, s[4:5]
	v_cndmask_b32_e64 v78, v78, v77, s[4:5]
	v_cndmask_b32_e64 v74, v74, v172, s[4:5]
	v_cndmask_b32_e64 v77, v77, 22, s[4:5]
	v_cndmask_b32_e64 v74, v74, v73, s[2:3]
	v_cndmask_b32_e64 v77, v77, v76, s[2:3]
	v_cndmask_b32_e64 v73, v73, v172, s[2:3]
	v_cndmask_b32_e64 v76, v76, 22, s[2:3]
	s_cmp_eq_u32 s14, 23
	s_cbranch_scc1 .Lgm_done
	v_cmp_gt_f32_e32 vcc, v173, v75
	v_cmp_gt_f32_e64 s[4:5], v173, v74
	v_cmp_gt_f32_e64 s[2:3], v173, v73
	v_cndmask_b32_e32 v75, v75, v173, vcc
	v_cndmask_b32_e64 v78, v78, 23, vcc
	v_cndmask_b32_e64 v75, v75, v74, s[4:5]
	v_cndmask_b32_e64 v78, v78, v77, s[4:5]
	v_cndmask_b32_e64 v74, v74, v173, s[4:5]
	v_cndmask_b32_e64 v77, v77, 23, s[4:5]
	v_cndmask_b32_e64 v74, v74, v73, s[2:3]
	v_cndmask_b32_e64 v77, v77, v76, s[2:3]
	v_cndmask_b32_e64 v73, v73, v173, s[2:3]
	v_cndmask_b32_e64 v76, v76, 23, s[2:3]
	s_cmp_eq_u32 s14, 24
	s_cbranch_scc1 .Lgm_done
	v_cmp_gt_f32_e32 vcc, v158, v75
	v_cmp_gt_f32_e64 s[4:5], v158, v74
	v_cmp_gt_f32_e64 s[2:3], v158, v73
	v_cndmask_b32_e32 v75, v75, v158, vcc
	v_cndmask_b32_e64 v78, v78, 24, vcc
	v_cndmask_b32_e64 v75, v75, v74, s[4:5]
	v_cndmask_b32_e64 v78, v78, v77, s[4:5]
	v_cndmask_b32_e64 v74, v74, v158, s[4:5]
	v_cndmask_b32_e64 v77, v77, 24, s[4:5]
	v_cndmask_b32_e64 v74, v74, v73, s[2:3]
	v_cndmask_b32_e64 v77, v77, v76, s[2:3]
	v_cndmask_b32_e64 v73, v73, v158, s[2:3]
	v_cndmask_b32_e64 v76, v76, 24, s[2:3]
	s_cmp_eq_u32 s14, 25
	s_cbranch_scc1 .Lgm_done
	v_cmp_gt_f32_e32 vcc, v159, v75
	v_cmp_gt_f32_e64 s[4:5], v159, v74
	v_cmp_gt_f32_e64 s[2:3], v159, v73
	v_cndmask_b32_e32 v75, v75, v159, vcc
	v_cndmask_b32_e64 v78, v78, 25, vcc
	v_cndmask_b32_e64 v75, v75, v74, s[4:5]
	v_cndmask_b32_e64 v78, v78, v77, s[4:5]
	v_cndmask_b32_e64 v74, v74, v159, s[4:5]
	v_cndmask_b32_e64 v77, v77, 25, s[4:5]
	v_cndmask_b32_e64 v74, v74, v73, s[2:3]
	v_cndmask_b32_e64 v77, v77, v76, s[2:3]
	v_cndmask_b32_e64 v73, v73, v159, s[2:3]
	v_cndmask_b32_e64 v76, v76, 25, s[2:3]
	s_cmp_eq_u32 s14, 26
	s_cbranch_scc1 .Lgm_done
	v_cmp_gt_f32_e32 vcc, v160, v75
	v_cmp_gt_f32_e64 s[4:5], v160, v74
	v_cmp_gt_f32_e64 s[2:3], v160, v73
	v_cndmask_b32_e32 v75, v75, v160, vcc
	v_cndmask_b32_e64 v78, v78, 26, vcc
	v_cndmask_b32_e64 v75, v75, v74, s[4:5]
	v_cndmask_b32_e64 v78, v78, v77, s[4:5]
	v_cndmask_b32_e64 v74, v74, v160, s[4:5]
	v_cndmask_b32_e64 v77, v77, 26, s[4:5]
	v_cndmask_b32_e64 v74, v74, v73, s[2:3]
	v_cndmask_b32_e64 v77, v77, v76, s[2:3]
	v_cndmask_b32_e64 v73, v73, v160, s[2:3]
	v_cndmask_b32_e64 v76, v76, 26, s[2:3]
	s_cmp_eq_u32 s14, 27
	s_cbranch_scc1 .Lgm_done
	v_cmp_gt_f32_e32 vcc, v161, v75
	v_cmp_gt_f32_e64 s[4:5], v161, v74
	v_cmp_gt_f32_e64 s[2:3], v161, v73
	v_cndmask_b32_e32 v75, v75, v161, vcc
	v_cndmask_b32_e64 v78, v78, 27, vcc
	v_cndmask_b32_e64 v75, v75, v74, s[4:5]
	v_cndmask_b32_e64 v78, v78, v77, s[4:5]
	v_cndmask_b32_e64 v74, v74, v161, s[4:5]
	v_cndmask_b32_e64 v77, v77, 27, s[4:5]
	v_cndmask_b32_e64 v74, v74, v73, s[2:3]
	v_cndmask_b32_e64 v77, v77, v76, s[2:3]
	v_cndmask_b32_e64 v73, v73, v161, s[2:3]
	v_cndmask_b32_e64 v76, v76, 27, s[2:3]
	s_cmp_eq_u32 s14, 28
	s_cbranch_scc1 .Lgm_done
	v_cmp_gt_f32_e32 vcc, v174, v75
	v_cmp_gt_f32_e64 s[4:5], v174, v74
	v_cmp_gt_f32_e64 s[2:3], v174, v73
	v_cndmask_b32_e32 v75, v75, v174, vcc
	v_cndmask_b32_e64 v78, v78, 28, vcc
	v_cndmask_b32_e64 v75, v75, v74, s[4:5]
	v_cndmask_b32_e64 v78, v78, v77, s[4:5]
	v_cndmask_b32_e64 v74, v74, v174, s[4:5]
	v_cndmask_b32_e64 v77, v77, 28, s[4:5]
	v_cndmask_b32_e64 v74, v74, v73, s[2:3]
	v_cndmask_b32_e64 v77, v77, v76, s[2:3]
	v_cndmask_b32_e64 v73, v73, v174, s[2:3]
	v_cndmask_b32_e64 v76, v76, 28, s[2:3]
	s_cmp_eq_u32 s14, 29
	s_cbranch_scc1 .Lgm_done
	v_cmp_gt_f32_e32 vcc, v175, v75
	v_cmp_gt_f32_e64 s[4:5], v175, v74
	v_cmp_gt_f32_e64 s[2:3], v175, v73
	v_cndmask_b32_e32 v75, v75, v175, vcc
	v_cndmask_b32_e64 v78, v78, 29, vcc
	v_cndmask_b32_e64 v75, v75, v74, s[4:5]
	v_cndmask_b32_e64 v78, v78, v77, s[4:5]
	v_cndmask_b32_e64 v74, v74, v175, s[4:5]
	v_cndmask_b32_e64 v77, v77, 29, s[4:5]
	v_cndmask_b32_e64 v74, v74, v73, s[2:3]
	v_cndmask_b32_e64 v77, v77, v76, s[2:3]
	v_cndmask_b32_e64 v73, v73, v175, s[2:3]
	v_cndmask_b32_e64 v76, v76, 29, s[2:3]
	s_cmp_eq_u32 s14, 30
	s_cbranch_scc1 .Lgm_done
	v_cmp_gt_f32_e32 vcc, v176, v75
	v_cmp_gt_f32_e64 s[4:5], v176, v74
	v_cmp_gt_f32_e64 s[2:3], v176, v73
	v_cndmask_b32_e32 v75, v75, v176, vcc
	v_cndmask_b32_e64 v78, v78, 30, vcc
	v_cndmask_b32_e64 v75, v75, v74, s[4:5]
	v_cndmask_b32_e64 v78, v78, v77, s[4:5]
	v_cndmask_b32_e64 v74, v74, v176, s[4:5]
	v_cndmask_b32_e64 v77, v77, 30, s[4:5]
	v_cndmask_b32_e64 v74, v74, v73, s[2:3]
	v_cndmask_b32_e64 v77, v77, v76, s[2:3]
	v_cndmask_b32_e64 v73, v73, v176, s[2:3]
	v_cndmask_b32_e64 v76, v76, 30, s[2:3]
.Lgm_done:
	v_lshlrev_b32_e32 v79, 8, v77
	v_lshlrev_b32_e32 v80, 16, v78
	v_or3_b32 v6, v79, v80, v76
	s_branch .LBB0_1085
